# lean hand-written SwiGLU epilogue (fewer VALU, folded rs scaling) on top of v8
# speedup vs baseline: 1.0098x; 1.0019x over previous
; __device__ __forceinline__ unsigned pk2(float lo, float hi) { f32x2_t v = {lo, hi}; bf16x2_t b = __builtin_convertvector(v, bf16x2_t); return __builtin_bit_cast(unsigned, b); }
; __device__ __forceinline__ float siluf_(float x) { return x * sigmoidf_(x); }
; #define RSTD_GET(ai, m) __int_as_float(__builtin_amdgcn_ds_bpermute(((m) * 16 + fr) << 2, __float_as_int((ai) ? es1 : es0)))
; __device__ __forceinline__ float row_rstd(const float* SS, int row) {
;     const f32x4* p = (const f32x4*)(SS + (size_t)row * 32);
;     float s = 0.f;
; #pragma unroll
;     for (int j = 0; j < 8; ++j) { const f32x4 a = p[j]; s += (a[0] + a[1]) + (a[2] + a[3]); }
;     return rsqrtf(s * (1.f / 1024.f) + EPS);
;     __device__ __forceinline__ void operator()(EPI_ARGS) const {
; #pragma unroll
;         for (int ai = 0; ai < 2; ++ai) {
;             if (ai == 1 && u.half) break;
; #pragma unroll
;             for (int m = 0; m < 4; ++m) {
;                 int row = EPI_ROWS(ai, m); asm volatile("" : "+v"(row)); const float rs = RSTD_GET(ai, m);
;                 float o[8];
; #pragma unroll
;                 for (int n = 0; n < 2; ++n)
; #pragma unroll
;                     for (int e = 0; e < 4; ++e) { const float g = acc[ai][0][m][n][e] * rs, up = acc[ai][1][m][n][e] * rs; o[n * 4 + e] = siluf_(g) * up; }
;                 u32x4 w; w.x = pk2(o[0], o[1]); w.y = pk2(o[2], o[3]); w.z = pk2(o[4], o[5]); w.w = pk2(o[6], o[7]);
;                 *(u32x4*)(T + (size_t)row * FF + u.pn * 128 + wc * 32 + 8 * fq) = w;
;             }
;         }
.LBB0_899:
	s_lshl_b32 s2, s63, 8
	v_mov_b32_e32 v247, 0
	v_add3_u32 v246, s2, v143, v142
	s_mov_b64 s[2:3], 0x4000
	v_lshlrev_b64 v[246:247], 7, v[246:247]
	v_lshl_add_u64 v[246:247], s[94:95], 0, v[246:247]
	v_lshl_add_u64 v[244:245], v[246:247], 0, s[2:3]
	global_load_dwordx4 v[204:207], v[246:247], off
	global_load_dwordx4 v[208:211], v[246:247], off offset:16
	global_load_dwordx4 v[212:215], v[246:247], off offset:32
	global_load_dwordx4 v[216:219], v[246:247], off offset:48
	global_load_dwordx4 v[220:223], v[246:247], off offset:64
	global_load_dwordx4 v[224:227], v[246:247], off offset:80
	global_load_dwordx4 v[228:231], v[246:247], off offset:96
	global_load_dwordx4 v[232:235], v[246:247], off offset:112
	global_load_dwordx4 v[236:239], v[244:245], off
	global_load_dwordx4 v[240:243], v[244:245], off offset:16
	global_load_dwordx4 v[180:183], v[244:245], off offset:32
	global_load_dwordx4 v[184:187], v[244:245], off offset:48
	global_load_dwordx4 v[190:193], v[244:245], off offset:64
	global_load_dwordx4 v[194:197], v[244:245], off offset:80
	global_load_dwordx4 v[160:163], v[244:245], off offset:96
	global_load_dwordx4 v[244:247], v[244:245], off offset:112
	s_lshl_b32 s26, s26, 8
	v_readlane_b32 s2, v255, 10
	v_readlane_b32 s3, v255, 11
	s_andn2_b64 vcc, exec, s[36:37]
	ds_bpermute_b32 v159, v145, v141
	v_add_u32_e32 v158, s26, v144
	s_nop 0
	v_mov_b64_e32 v[156:157], s[2:3]
	s_nop 0
	v_mad_i64_i32 v[154:155], s[38:39], v158, s71, v[156:157]
	s_lshl_b32 s2, s27, 7
	s_ashr_i32 s3, s2, 31
	s_lshl_b64 s[2:3], s[2:3], 1
	v_lshl_add_u64 v[154:155], v[154:155], 0, s[2:3]
	v_lshl_add_u64 v[154:155], v[154:155], 0, s[4:5]
	v_lshl_add_u64 v[154:155], v[154:155], 0, v[168:169]
	s_mov_b64 s[38:39], 0x16000
	s_waitcnt lgkmcnt(0)
	v_mul_f32_e32 v156, 0xbfb8aa3b, v159
	v_mul_f32_e32 v158, v159, v159
	ds_bpermute_b32 v159, v148, v141
	v_pk_mul_f32 v[120:121], v[120:121], v[124:125]
	v_pk_mul_f32 v[122:123], v[122:123], v[126:127]
	v_pk_mul_f32 v[112:113], v[112:113], v[116:117]
	v_pk_mul_f32 v[114:115], v[114:115], v[118:119]
	v_pk_mul_f32 v[124:125], v[124:125], v[156:157] op_sel_hi:[1,0]
	v_pk_mul_f32 v[126:127], v[126:127], v[156:157] op_sel_hi:[1,0]
	v_pk_mul_f32 v[116:117], v[116:117], v[156:157] op_sel_hi:[1,0]
	v_pk_mul_f32 v[118:119], v[118:119], v[156:157] op_sel_hi:[1,0]
	v_exp_f32_e32 v124, v124
	v_exp_f32_e32 v125, v125
	v_exp_f32_e32 v126, v126
	v_exp_f32_e32 v127, v127
	v_exp_f32_e32 v116, v116
	v_exp_f32_e32 v117, v117
	v_exp_f32_e32 v118, v118
	v_exp_f32_e32 v119, v119
	v_pk_add_f32 v[124:125], v[124:125], 1.0 op_sel_hi:[1,0]
	v_pk_add_f32 v[126:127], v[126:127], 1.0 op_sel_hi:[1,0]
	v_pk_add_f32 v[116:117], v[116:117], 1.0 op_sel_hi:[1,0]
	v_pk_add_f32 v[118:119], v[118:119], 1.0 op_sel_hi:[1,0]
	v_rcp_f32_e32 v124, v124
	v_rcp_f32_e32 v125, v125
	v_rcp_f32_e32 v126, v126
	v_rcp_f32_e32 v127, v127
	v_rcp_f32_e32 v116, v116
	v_rcp_f32_e32 v117, v117
	v_rcp_f32_e32 v118, v118
	v_rcp_f32_e32 v119, v119
	v_pk_mul_f32 v[120:121], v[120:121], v[158:159] op_sel_hi:[1,0]
	v_pk_mul_f32 v[122:123], v[122:123], v[158:159] op_sel_hi:[1,0]
	v_pk_mul_f32 v[112:113], v[112:113], v[158:159] op_sel_hi:[1,0]
	v_pk_mul_f32 v[114:115], v[114:115], v[158:159] op_sel_hi:[1,0]
	v_pk_mul_f32 v[120:121], v[120:121], v[124:125]
	v_pk_mul_f32 v[122:123], v[122:123], v[126:127]
	v_pk_mul_f32 v[112:113], v[112:113], v[116:117]
	v_pk_mul_f32 v[114:115], v[114:115], v[118:119]
	v_cvt_pk_bf16_f32 v124, v120, v121
	v_cvt_pk_bf16_f32 v125, v122, v123
	v_cvt_pk_bf16_f32 v126, v112, v113
	v_cvt_pk_bf16_f32 v127, v114, v115
	global_store_dwordx4 v[154:155], v[124:127], off
	v_lshl_add_u64 v[154:155], v[154:155], 0, s[38:39]
	s_waitcnt lgkmcnt(0)
	v_mul_f32_e32 v156, 0xbfb8aa3b, v159
	v_mul_f32_e32 v158, v159, v159
	ds_bpermute_b32 v159, v150, v141
	v_pk_mul_f32 v[104:105], v[104:105], v[108:109]
	v_pk_mul_f32 v[106:107], v[106:107], v[110:111]
	v_pk_mul_f32 v[96:97], v[96:97], v[100:101]
	v_pk_mul_f32 v[98:99], v[98:99], v[102:103]
	v_pk_mul_f32 v[108:109], v[108:109], v[156:157] op_sel_hi:[1,0]
	v_pk_mul_f32 v[110:111], v[110:111], v[156:157] op_sel_hi:[1,0]
	v_pk_mul_f32 v[100:101], v[100:101], v[156:157] op_sel_hi:[1,0]
	v_pk_mul_f32 v[102:103], v[102:103], v[156:157] op_sel_hi:[1,0]
	v_exp_f32_e32 v108, v108
	v_exp_f32_e32 v109, v109
	v_exp_f32_e32 v110, v110
	v_exp_f32_e32 v111, v111
	v_exp_f32_e32 v100, v100
	v_exp_f32_e32 v101, v101
	v_exp_f32_e32 v102, v102
	v_exp_f32_e32 v103, v103
	v_pk_add_f32 v[108:109], v[108:109], 1.0 op_sel_hi:[1,0]
	v_pk_add_f32 v[110:111], v[110:111], 1.0 op_sel_hi:[1,0]
	v_pk_add_f32 v[100:101], v[100:101], 1.0 op_sel_hi:[1,0]
	v_pk_add_f32 v[102:103], v[102:103], 1.0 op_sel_hi:[1,0]
	v_rcp_f32_e32 v108, v108
	v_rcp_f32_e32 v109, v109
	v_rcp_f32_e32 v110, v110
	v_rcp_f32_e32 v111, v111
	v_rcp_f32_e32 v100, v100
	v_rcp_f32_e32 v101, v101
	v_rcp_f32_e32 v102, v102
	v_rcp_f32_e32 v103, v103
	v_pk_mul_f32 v[104:105], v[104:105], v[158:159] op_sel_hi:[1,0]
	v_pk_mul_f32 v[106:107], v[106:107], v[158:159] op_sel_hi:[1,0]
	v_pk_mul_f32 v[96:97], v[96:97], v[158:159] op_sel_hi:[1,0]
	v_pk_mul_f32 v[98:99], v[98:99], v[158:159] op_sel_hi:[1,0]
	v_pk_mul_f32 v[104:105], v[104:105], v[108:109]
	v_pk_mul_f32 v[106:107], v[106:107], v[110:111]
	v_pk_mul_f32 v[96:97], v[96:97], v[100:101]
	v_pk_mul_f32 v[98:99], v[98:99], v[102:103]
	v_cvt_pk_bf16_f32 v108, v104, v105
	v_cvt_pk_bf16_f32 v109, v106, v107
	v_cvt_pk_bf16_f32 v110, v96, v97
	v_cvt_pk_bf16_f32 v111, v98, v99
	global_store_dwordx4 v[154:155], v[108:111], off
	v_lshl_add_u64 v[154:155], v[154:155], 0, s[38:39]
	s_waitcnt lgkmcnt(0)
; __device__ __forceinline__ unsigned pk2(float lo, float hi) { f32x2_t v = {lo, hi}; bf16x2_t b = __builtin_convertvector(v, bf16x2_t); return __builtin_bit_cast(unsigned, b); }
; __device__ __forceinline__ float siluf_(float x) { return x * sigmoidf_(x); }
; #define RSTD_GET(ai, m) __int_as_float(__builtin_amdgcn_ds_bpermute(((m) * 16 + fr) << 2, __float_as_int((ai) ? es1 : es0)))
;     __device__ __forceinline__ void operator()(EPI_ARGS) const {
;     ...
;             for (int m = 0; m < 4; ++m) {
;                 int row = EPI_ROWS(ai, m); asm volatile("" : "+v"(row)); const float rs = RSTD_GET(ai, m);
;                 float o[8];
; #pragma unroll
;                 for (int n = 0; n < 2; ++n)
; #pragma unroll
;                     for (int e = 0; e < 4; ++e) { const float g = acc[ai][0][m][n][e] * rs, up = acc[ai][1][m][n][e] * rs; o[n * 4 + e] = siluf_(g) * up; }
;                 u32x4 w; w.x = pk2(o[0], o[1]); w.y = pk2(o[2], o[3]); w.z = pk2(o[4], o[5]); w.w = pk2(o[6], o[7]);
;                 *(u32x4*)(T + (size_t)row * FF + u.pn * 128 + wc * 32 + 8 * fq) = w;
	v_mul_f32_e32 v156, 0xbfb8aa3b, v159
	v_mul_f32_e32 v158, v159, v159
	ds_bpermute_b32 v159, v152, v141
	v_pk_mul_f32 v[88:89], v[88:89], v[92:93]
	v_pk_mul_f32 v[90:91], v[90:91], v[94:95]
	v_pk_mul_f32 v[80:81], v[80:81], v[84:85]
	v_pk_mul_f32 v[82:83], v[82:83], v[86:87]
	v_pk_mul_f32 v[92:93], v[92:93], v[156:157] op_sel_hi:[1,0]
	v_pk_mul_f32 v[94:95], v[94:95], v[156:157] op_sel_hi:[1,0]
	v_pk_mul_f32 v[84:85], v[84:85], v[156:157] op_sel_hi:[1,0]
	v_pk_mul_f32 v[86:87], v[86:87], v[156:157] op_sel_hi:[1,0]
	v_exp_f32_e32 v92, v92
	v_exp_f32_e32 v93, v93
	v_exp_f32_e32 v94, v94
	v_exp_f32_e32 v95, v95
	v_exp_f32_e32 v84, v84
	v_exp_f32_e32 v85, v85
	v_exp_f32_e32 v86, v86
	v_exp_f32_e32 v87, v87
	v_pk_add_f32 v[92:93], v[92:93], 1.0 op_sel_hi:[1,0]
	v_pk_add_f32 v[94:95], v[94:95], 1.0 op_sel_hi:[1,0]
	v_pk_add_f32 v[84:85], v[84:85], 1.0 op_sel_hi:[1,0]
	v_pk_add_f32 v[86:87], v[86:87], 1.0 op_sel_hi:[1,0]
	v_rcp_f32_e32 v92, v92
	v_rcp_f32_e32 v93, v93
	v_rcp_f32_e32 v94, v94
	v_rcp_f32_e32 v95, v95
	v_rcp_f32_e32 v84, v84
	v_rcp_f32_e32 v85, v85
	v_rcp_f32_e32 v86, v86
	v_rcp_f32_e32 v87, v87
	v_pk_mul_f32 v[88:89], v[88:89], v[158:159] op_sel_hi:[1,0]
	v_pk_mul_f32 v[90:91], v[90:91], v[158:159] op_sel_hi:[1,0]
	v_pk_mul_f32 v[80:81], v[80:81], v[158:159] op_sel_hi:[1,0]
	v_pk_mul_f32 v[82:83], v[82:83], v[158:159] op_sel_hi:[1,0]
	v_pk_mul_f32 v[88:89], v[88:89], v[92:93]
	v_pk_mul_f32 v[90:91], v[90:91], v[94:95]
	v_pk_mul_f32 v[80:81], v[80:81], v[84:85]
	v_pk_mul_f32 v[82:83], v[82:83], v[86:87]
	v_cvt_pk_bf16_f32 v92, v88, v89
	v_cvt_pk_bf16_f32 v93, v90, v91
	v_cvt_pk_bf16_f32 v94, v80, v81
	v_cvt_pk_bf16_f32 v95, v82, v83
	global_store_dwordx4 v[154:155], v[92:95], off
	v_lshl_add_u64 v[154:155], v[154:155], 0, s[38:39]
	s_waitcnt lgkmcnt(0)
	v_mul_f32_e32 v156, 0xbfb8aa3b, v159
	v_mul_f32_e32 v158, v159, v159
	ds_bpermute_b32 v159, v145, v140
	v_pk_mul_f32 v[72:73], v[72:73], v[76:77]
	v_pk_mul_f32 v[74:75], v[74:75], v[78:79]
	v_pk_mul_f32 v[64:65], v[64:65], v[68:69]
	v_pk_mul_f32 v[66:67], v[66:67], v[70:71]
	v_pk_mul_f32 v[76:77], v[76:77], v[156:157] op_sel_hi:[1,0]
	v_pk_mul_f32 v[78:79], v[78:79], v[156:157] op_sel_hi:[1,0]
	v_pk_mul_f32 v[68:69], v[68:69], v[156:157] op_sel_hi:[1,0]
	v_pk_mul_f32 v[70:71], v[70:71], v[156:157] op_sel_hi:[1,0]
	v_exp_f32_e32 v76, v76
	v_exp_f32_e32 v77, v77
	v_exp_f32_e32 v78, v78
	v_exp_f32_e32 v79, v79
	v_exp_f32_e32 v68, v68
	v_exp_f32_e32 v69, v69
	v_exp_f32_e32 v70, v70
	v_exp_f32_e32 v71, v71
	v_pk_add_f32 v[76:77], v[76:77], 1.0 op_sel_hi:[1,0]
	v_pk_add_f32 v[78:79], v[78:79], 1.0 op_sel_hi:[1,0]
	v_pk_add_f32 v[68:69], v[68:69], 1.0 op_sel_hi:[1,0]
	v_pk_add_f32 v[70:71], v[70:71], 1.0 op_sel_hi:[1,0]
	v_rcp_f32_e32 v76, v76
	v_rcp_f32_e32 v77, v77
	v_rcp_f32_e32 v78, v78
	v_rcp_f32_e32 v79, v79
	v_rcp_f32_e32 v68, v68
	v_rcp_f32_e32 v69, v69
	v_rcp_f32_e32 v70, v70
	v_rcp_f32_e32 v71, v71
	v_pk_mul_f32 v[72:73], v[72:73], v[158:159] op_sel_hi:[1,0]
	v_pk_mul_f32 v[74:75], v[74:75], v[158:159] op_sel_hi:[1,0]
	v_pk_mul_f32 v[64:65], v[64:65], v[158:159] op_sel_hi:[1,0]
	v_pk_mul_f32 v[66:67], v[66:67], v[158:159] op_sel_hi:[1,0]
	v_pk_mul_f32 v[72:73], v[72:73], v[76:77]
	v_pk_mul_f32 v[74:75], v[74:75], v[78:79]
	v_pk_mul_f32 v[64:65], v[64:65], v[68:69]
	v_pk_mul_f32 v[66:67], v[66:67], v[70:71]
	v_cvt_pk_bf16_f32 v76, v72, v73
	v_cvt_pk_bf16_f32 v77, v74, v75
	v_cvt_pk_bf16_f32 v78, v64, v65
	v_cvt_pk_bf16_f32 v79, v66, v67
	s_mov_b64 s[38:39], 0x6e000
	global_store_dwordx4 v[154:155], v[76:79], off
	v_lshl_add_u64 v[154:155], v[154:155], 0, s[38:39]
	s_mov_b64 s[38:39], 0x16000
	s_waitcnt lgkmcnt(0)
	v_mul_f32_e32 v156, 0xbfb8aa3b, v159
	v_mul_f32_e32 v158, v159, v159
	ds_bpermute_b32 v159, v148, v140
	v_pk_mul_f32 v[56:57], v[56:57], v[60:61]
	v_pk_mul_f32 v[58:59], v[58:59], v[62:63]
	v_pk_mul_f32 v[48:49], v[48:49], v[52:53]
	v_pk_mul_f32 v[50:51], v[50:51], v[54:55]
	v_pk_mul_f32 v[60:61], v[60:61], v[156:157] op_sel_hi:[1,0]
	v_pk_mul_f32 v[62:63], v[62:63], v[156:157] op_sel_hi:[1,0]
	v_pk_mul_f32 v[52:53], v[52:53], v[156:157] op_sel_hi:[1,0]
	v_pk_mul_f32 v[54:55], v[54:55], v[156:157] op_sel_hi:[1,0]
	v_exp_f32_e32 v60, v60
	v_exp_f32_e32 v61, v61
	v_exp_f32_e32 v62, v62
	v_exp_f32_e32 v63, v63
	v_exp_f32_e32 v52, v52
	v_exp_f32_e32 v53, v53
	v_exp_f32_e32 v54, v54
	v_exp_f32_e32 v55, v55
	v_pk_add_f32 v[60:61], v[60:61], 1.0 op_sel_hi:[1,0]
	v_pk_add_f32 v[62:63], v[62:63], 1.0 op_sel_hi:[1,0]
	v_pk_add_f32 v[52:53], v[52:53], 1.0 op_sel_hi:[1,0]
	v_pk_add_f32 v[54:55], v[54:55], 1.0 op_sel_hi:[1,0]
	v_rcp_f32_e32 v60, v60
	v_rcp_f32_e32 v61, v61
	v_rcp_f32_e32 v62, v62
	v_rcp_f32_e32 v63, v63
	v_rcp_f32_e32 v52, v52
	v_rcp_f32_e32 v53, v53
	v_rcp_f32_e32 v54, v54
	v_rcp_f32_e32 v55, v55
	v_pk_mul_f32 v[56:57], v[56:57], v[158:159] op_sel_hi:[1,0]
	v_pk_mul_f32 v[58:59], v[58:59], v[158:159] op_sel_hi:[1,0]
	v_pk_mul_f32 v[48:49], v[48:49], v[158:159] op_sel_hi:[1,0]
	v_pk_mul_f32 v[50:51], v[50:51], v[158:159] op_sel_hi:[1,0]
	v_pk_mul_f32 v[56:57], v[56:57], v[60:61]
	v_pk_mul_f32 v[58:59], v[58:59], v[62:63]
	v_pk_mul_f32 v[48:49], v[48:49], v[52:53]
	v_pk_mul_f32 v[50:51], v[50:51], v[54:55]
	v_cvt_pk_bf16_f32 v60, v56, v57
	v_cvt_pk_bf16_f32 v61, v58, v59
	v_cvt_pk_bf16_f32 v62, v48, v49
	v_cvt_pk_bf16_f32 v63, v50, v51
	global_store_dwordx4 v[154:155], v[60:63], off
	v_lshl_add_u64 v[154:155], v[154:155], 0, s[38:39]
	s_waitcnt lgkmcnt(0)
; __device__ __forceinline__ unsigned pk2(float lo, float hi) { f32x2_t v = {lo, hi}; bf16x2_t b = __builtin_convertvector(v, bf16x2_t); return __builtin_bit_cast(unsigned, b); }
; __device__ __forceinline__ float siluf_(float x) { return x * sigmoidf_(x); }
; #define RSTD_GET(ai, m) __int_as_float(__builtin_amdgcn_ds_bpermute(((m) * 16 + fr) << 2, __float_as_int((ai) ? es1 : es0)))
; template <class Epi, class Sched>
; __device__ __forceinline__ void gemm_phase(const int tid, LAS unsigned char* lds, const int lda, const int ldb, const int K, const Sched& S, const Epi& E) {
;     ...
;         if (!has_next) break;
;     __device__ __forceinline__ void operator()(EPI_ARGS) const {
;     ...
;             for (int m = 0; m < 4; ++m) {
;                 int row = EPI_ROWS(ai, m); asm volatile("" : "+v"(row)); const float rs = RSTD_GET(ai, m);
;                 float o[8];
; #pragma unroll
;                 for (int n = 0; n < 2; ++n)
; #pragma unroll
;                     for (int e = 0; e < 4; ++e) { const float g = acc[ai][0][m][n][e] * rs, up = acc[ai][1][m][n][e] * rs; o[n * 4 + e] = siluf_(g) * up; }
;                 u32x4 w; w.x = pk2(o[0], o[1]); w.y = pk2(o[2], o[3]); w.z = pk2(o[4], o[5]); w.w = pk2(o[6], o[7]);
;                 *(u32x4*)(T + (size_t)row * FF + u.pn * 128 + wc * 32 + 8 * fq) = w;
	v_mul_f32_e32 v156, 0xbfb8aa3b, v159
	v_mul_f32_e32 v158, v159, v159
	ds_bpermute_b32 v159, v150, v140
	v_pk_mul_f32 v[40:41], v[40:41], v[44:45]
	v_pk_mul_f32 v[42:43], v[42:43], v[46:47]
	v_pk_mul_f32 v[32:33], v[32:33], v[36:37]
	v_pk_mul_f32 v[34:35], v[34:35], v[38:39]
	v_pk_mul_f32 v[44:45], v[44:45], v[156:157] op_sel_hi:[1,0]
	v_pk_mul_f32 v[46:47], v[46:47], v[156:157] op_sel_hi:[1,0]
	v_pk_mul_f32 v[36:37], v[36:37], v[156:157] op_sel_hi:[1,0]
	v_pk_mul_f32 v[38:39], v[38:39], v[156:157] op_sel_hi:[1,0]
	v_exp_f32_e32 v44, v44
	v_exp_f32_e32 v45, v45
	v_exp_f32_e32 v46, v46
	v_exp_f32_e32 v47, v47
	v_exp_f32_e32 v36, v36
	v_exp_f32_e32 v37, v37
	v_exp_f32_e32 v38, v38
	v_exp_f32_e32 v39, v39
	v_pk_add_f32 v[44:45], v[44:45], 1.0 op_sel_hi:[1,0]
	v_pk_add_f32 v[46:47], v[46:47], 1.0 op_sel_hi:[1,0]
	v_pk_add_f32 v[36:37], v[36:37], 1.0 op_sel_hi:[1,0]
	v_pk_add_f32 v[38:39], v[38:39], 1.0 op_sel_hi:[1,0]
	v_rcp_f32_e32 v44, v44
	v_rcp_f32_e32 v45, v45
	v_rcp_f32_e32 v46, v46
	v_rcp_f32_e32 v47, v47
	v_rcp_f32_e32 v36, v36
	v_rcp_f32_e32 v37, v37
	v_rcp_f32_e32 v38, v38
	v_rcp_f32_e32 v39, v39
	v_pk_mul_f32 v[40:41], v[40:41], v[158:159] op_sel_hi:[1,0]
	v_pk_mul_f32 v[42:43], v[42:43], v[158:159] op_sel_hi:[1,0]
	v_pk_mul_f32 v[32:33], v[32:33], v[158:159] op_sel_hi:[1,0]
	v_pk_mul_f32 v[34:35], v[34:35], v[158:159] op_sel_hi:[1,0]
	v_pk_mul_f32 v[40:41], v[40:41], v[44:45]
	v_pk_mul_f32 v[42:43], v[42:43], v[46:47]
	v_pk_mul_f32 v[32:33], v[32:33], v[36:37]
	v_pk_mul_f32 v[34:35], v[34:35], v[38:39]
	v_cvt_pk_bf16_f32 v44, v40, v41
	v_cvt_pk_bf16_f32 v45, v42, v43
	v_cvt_pk_bf16_f32 v46, v32, v33
	v_cvt_pk_bf16_f32 v47, v34, v35
	global_store_dwordx4 v[154:155], v[44:47], off
	v_lshl_add_u64 v[154:155], v[154:155], 0, s[38:39]
	s_waitcnt lgkmcnt(0)
	v_mul_f32_e32 v156, 0xbfb8aa3b, v159
	v_mul_f32_e32 v158, v159, v159
	ds_bpermute_b32 v159, v152, v140
	v_pk_mul_f32 v[24:25], v[24:25], v[28:29]
	v_pk_mul_f32 v[26:27], v[26:27], v[30:31]
	v_pk_mul_f32 v[16:17], v[16:17], v[20:21]
	v_pk_mul_f32 v[18:19], v[18:19], v[22:23]
	v_pk_mul_f32 v[28:29], v[28:29], v[156:157] op_sel_hi:[1,0]
	v_pk_mul_f32 v[30:31], v[30:31], v[156:157] op_sel_hi:[1,0]
	v_pk_mul_f32 v[20:21], v[20:21], v[156:157] op_sel_hi:[1,0]
	v_pk_mul_f32 v[22:23], v[22:23], v[156:157] op_sel_hi:[1,0]
	v_exp_f32_e32 v28, v28
	v_exp_f32_e32 v29, v29
	v_exp_f32_e32 v30, v30
	v_exp_f32_e32 v31, v31
	v_exp_f32_e32 v20, v20
	v_exp_f32_e32 v21, v21
	v_exp_f32_e32 v22, v22
	v_exp_f32_e32 v23, v23
	v_pk_add_f32 v[28:29], v[28:29], 1.0 op_sel_hi:[1,0]
	v_pk_add_f32 v[30:31], v[30:31], 1.0 op_sel_hi:[1,0]
	v_pk_add_f32 v[20:21], v[20:21], 1.0 op_sel_hi:[1,0]
	v_pk_add_f32 v[22:23], v[22:23], 1.0 op_sel_hi:[1,0]
	v_rcp_f32_e32 v28, v28
	v_rcp_f32_e32 v29, v29
	v_rcp_f32_e32 v30, v30
	v_rcp_f32_e32 v31, v31
	v_rcp_f32_e32 v20, v20
	v_rcp_f32_e32 v21, v21
	v_rcp_f32_e32 v22, v22
	v_rcp_f32_e32 v23, v23
	v_pk_mul_f32 v[24:25], v[24:25], v[158:159] op_sel_hi:[1,0]
	v_pk_mul_f32 v[26:27], v[26:27], v[158:159] op_sel_hi:[1,0]
	v_pk_mul_f32 v[16:17], v[16:17], v[158:159] op_sel_hi:[1,0]
	v_pk_mul_f32 v[18:19], v[18:19], v[158:159] op_sel_hi:[1,0]
	v_pk_mul_f32 v[24:25], v[24:25], v[28:29]
	v_pk_mul_f32 v[26:27], v[26:27], v[30:31]
	v_pk_mul_f32 v[16:17], v[16:17], v[20:21]
	v_pk_mul_f32 v[18:19], v[18:19], v[22:23]
	v_cvt_pk_bf16_f32 v28, v24, v25
	v_cvt_pk_bf16_f32 v29, v26, v27
	v_cvt_pk_bf16_f32 v30, v16, v17
	v_cvt_pk_bf16_f32 v31, v18, v19
	global_store_dwordx4 v[154:155], v[28:31], off
	v_lshl_add_u64 v[154:155], v[154:155], 0, s[38:39]
	s_waitcnt lgkmcnt(0)
	v_mul_f32_e32 v156, 0xbfb8aa3b, v159
	v_mul_f32_e32 v158, v159, v159
	v_pk_mul_f32 v[8:9], v[8:9], v[12:13]
	v_pk_mul_f32 v[10:11], v[10:11], v[14:15]
	v_pk_mul_f32 v[0:1], v[0:1], v[4:5]
	v_pk_mul_f32 v[2:3], v[2:3], v[6:7]
	v_pk_mul_f32 v[12:13], v[12:13], v[156:157] op_sel_hi:[1,0]
	v_pk_mul_f32 v[14:15], v[14:15], v[156:157] op_sel_hi:[1,0]
	v_pk_mul_f32 v[4:5], v[4:5], v[156:157] op_sel_hi:[1,0]
	v_pk_mul_f32 v[6:7], v[6:7], v[156:157] op_sel_hi:[1,0]
	v_exp_f32_e32 v12, v12
	v_exp_f32_e32 v13, v13
	v_exp_f32_e32 v14, v14
	v_exp_f32_e32 v15, v15
	v_exp_f32_e32 v4, v4
	v_exp_f32_e32 v5, v5
	v_exp_f32_e32 v6, v6
	v_exp_f32_e32 v7, v7
	v_pk_add_f32 v[12:13], v[12:13], 1.0 op_sel_hi:[1,0]
	v_pk_add_f32 v[14:15], v[14:15], 1.0 op_sel_hi:[1,0]
	v_pk_add_f32 v[4:5], v[4:5], 1.0 op_sel_hi:[1,0]
	v_pk_add_f32 v[6:7], v[6:7], 1.0 op_sel_hi:[1,0]
	v_rcp_f32_e32 v12, v12
	v_rcp_f32_e32 v13, v13
	v_rcp_f32_e32 v14, v14
	v_rcp_f32_e32 v15, v15
	v_rcp_f32_e32 v4, v4
	v_rcp_f32_e32 v5, v5
	v_rcp_f32_e32 v6, v6
	v_rcp_f32_e32 v7, v7
	v_pk_mul_f32 v[8:9], v[8:9], v[158:159] op_sel_hi:[1,0]
	v_pk_mul_f32 v[10:11], v[10:11], v[158:159] op_sel_hi:[1,0]
	v_pk_mul_f32 v[0:1], v[0:1], v[158:159] op_sel_hi:[1,0]
	v_pk_mul_f32 v[2:3], v[2:3], v[158:159] op_sel_hi:[1,0]
	v_pk_mul_f32 v[8:9], v[8:9], v[12:13]
	v_pk_mul_f32 v[10:11], v[10:11], v[14:15]
	v_pk_mul_f32 v[0:1], v[0:1], v[4:5]
	v_pk_mul_f32 v[2:3], v[2:3], v[6:7]
	v_cvt_pk_bf16_f32 v12, v8, v9
	v_cvt_pk_bf16_f32 v13, v10, v11
	v_cvt_pk_bf16_f32 v14, v0, v1
	v_cvt_pk_bf16_f32 v15, v2, v3
	s_mov_b64 s[2:3], -1
	global_store_dwordx4 v[154:155], v[12:15], off
	s_cbranch_vccnz .LBB0_891
; #define PG8_BAR __builtin_amdgcn_s_barrier()
; template <class Epi, class Sched>
; __device__ __forceinline__ void gemm_phase(const int tid, LAS unsigned char* lds, const int lda, const int ldb, const int K, const Sched& S, const Epi& E) {
;     ...
;         E.pre(nxt, wr, wc, fr, fq, es0, es1);
;         E.init(acc, nxt, wr, wc, fr, fq);
;         cur = nxt; cA = nA; cB = nB; ++ui;
;         if (wr == 1) PG8_BAR;
; __device__ __forceinline__ float row_rstd(const float* SS, int row) {
;     const f32x4* p = (const f32x4*)(SS + (size_t)row * 32);
;     float s = 0.f;
; #pragma unroll
;     for (int j = 0; j < 8; ++j) { const f32x4 a = p[j]; s += (a[0] + a[1]) + (a[2] + a[3]); }
;     return rsqrtf(s * (1.f / 1024.f) + EPS);
	s_waitcnt vmcnt(8)
	v_add_f32_e32 v4, v204, v205
	v_add_f32_e32 v6, v236, v237
	v_add_f32_e32 v5, v206, v207
	v_add_f32_e32 v7, v238, v239
	v_add_f32_e32 v1, v4, v5
	v_add_f32_e32 v0, v6, v7
	v_add_f32_e32 v1, 0, v1
	v_add_f32_e32 v0, 0, v0
	v_add_f32_e32 v4, v208, v209
	v_add_f32_e32 v6, v240, v241
	v_add_f32_e32 v5, v210, v211
	v_add_f32_e32 v7, v242, v243
	v_add_f32_e32 v4, v4, v5
	v_add_f32_e32 v6, v6, v7
	v_add_f32_e32 v1, v1, v4
	v_add_f32_e32 v0, v0, v6
	v_add_f32_e32 v4, v212, v213
	v_add_f32_e32 v6, v180, v181
	v_add_f32_e32 v5, v214, v215
	v_add_f32_e32 v7, v182, v183
	v_add_f32_e32 v4, v4, v5
	v_add_f32_e32 v6, v6, v7
	v_add_f32_e32 v1, v1, v4
	v_add_f32_e32 v0, v0, v6
	v_add_f32_e32 v4, v216, v217
	v_add_f32_e32 v6, v184, v185
	v_add_f32_e32 v5, v218, v219
	v_add_f32_e32 v7, v186, v187
	v_add_f32_e32 v4, v4, v5
	v_add_f32_e32 v6, v6, v7
	v_add_f32_e32 v1, v1, v4
	v_add_f32_e32 v0, v0, v6
	v_add_f32_e32 v4, v220, v221
	v_add_f32_e32 v6, v190, v191
	v_add_f32_e32 v5, v222, v223
	v_add_f32_e32 v7, v192, v193
	v_add_f32_e32 v4, v4, v5
	v_add_f32_e32 v6, v6, v7
	v_add_f32_e32 v1, v1, v4
	v_add_f32_e32 v0, v0, v6
	v_add_f32_e32 v4, v224, v225
	v_add_f32_e32 v6, v194, v195
	v_add_f32_e32 v5, v226, v227
	v_add_f32_e32 v7, v196, v197
	v_add_f32_e32 v4, v4, v5
	v_add_f32_e32 v6, v6, v7
	v_add_f32_e32 v1, v1, v4
	v_add_f32_e32 v0, v0, v6
	v_add_f32_e32 v4, v228, v229
	v_add_f32_e32 v6, v160, v161
	v_add_f32_e32 v5, v230, v231
	v_add_f32_e32 v7, v162, v163
	v_add_f32_e32 v4, v4, v5
	v_add_f32_e32 v6, v6, v7
	v_add_f32_e32 v1, v1, v4
	v_add_f32_e32 v0, v0, v6
	v_add_f32_e32 v4, v232, v233
	v_add_f32_e32 v6, v244, v245
	v_add_f32_e32 v5, v234, v235
	v_add_f32_e32 v7, v246, v247
	v_add_f32_e32 v4, v4, v5
	v_add_f32_e32 v6, v6, v7
	v_add_f32_e32 v1, v1, v4
	v_add_f32_e32 v0, v0, v6
	s_mov_b32 s2, 0x3a800000
	s_andn2_b64 vcc, exec, s[22:23]
	s_nop 0
	v_pk_fma_f32 v[0:1], v[0:1], s[2:3], v[170:171] op_sel_hi:[1,0,0]
	s_nop 0
	v_cmp_gt_f32_e64 s[36:37], s33, v0
	v_cmp_gt_f32_e64 s[38:39], s33, v1
	s_cbranch_vccnz .LBB0_890
	s_barrier
	s_branch .LBB0_890
